# gemm1: tile epilogue stores deferred into the next tile's k-loop (4 stores at k-tiles 0,4,8,12), flushed at phase end
# speedup vs baseline: 1.0039x; 1.0039x over previous
.LBB0_141:
	s_or_b64 exec, exec, s[0:1]
	s_mov_b32 s101, 0
	s_and_b32 s0, s28, 7
	s_cmp_lg_u32 s0, 0
	s_cselect_b64 s[4:5], -1, 0
	v_mov_b32_e32 v98, v174
	s_waitcnt lgkmcnt(0)
	v_mov_b32_e32 v0, v174
	v_writelane_b32 v254, s4, 56
	s_barrier
	s_nop 0
	v_writelane_b32 v254, s5, 57
	v_ashrrev_i32_e32 v99, 7, v0
	s_cmp_eq_u32 s0, 0
	v_bfe_u32 v100, v0, 6, 1
	s_cbranch_scc1 .LBB0_150
	s_cmpk_gt_i32 s2, 0xfef
	s_cbranch_scc1 .LBB0_149
	v_and_b32_e32 v0, 15, v98
	v_lshl_or_b32 v101, v99, 6, v0
	v_lshrrev_b32_e32 v0, 2, v98
	v_and_b32_e32 v0, 12, v0
	v_lshl_or_b32 v102, v100, 6, v0
	v_mov_b32_e32 v65, 0
	s_mov_b64 s[0:1], 0x80
	s_mov_b64 s[4:5], 0x100
	s_movk_i32 s3, 0x1e20
	s_mov_b32 s86, s2
	s_branch .LBB0_145

.LBB0_153:
	v_lshl_add_u32 v64, s8, 7, v99
	v_lshl_or_b32 v66, s6, 7, v98
	v_cvt_pk_f16_f32 v63, v62, v63
	v_cvt_pk_f16_f32 v62, v60, v61
	v_mov_b64_e32 v[60:61], s[42:43]
	v_ashrrev_i32_e32 v67, 31, v66
	v_cvt_pk_f16_f32 v51, v50, v51
	v_cvt_pk_f16_f32 v50, v48, v49
	v_or_b32_e32 v48, 16, v64
	v_cvt_pk_f16_f32 v35, v34, v35
	v_cvt_pk_f16_f32 v34, v32, v33
	v_or_b32_e32 v32, 32, v64
	v_cvt_pk_f16_f32 v19, v18, v19
	v_cvt_pk_f16_f32 v18, v16, v17
	v_or_b32_e32 v16, 48, v64
	v_mad_i64_i32 v[68:69], s[6:7], v64, s87, v[60:61]
	v_lshlrev_b64 v[66:67], 1, v[66:67]
	v_cvt_pk_f16_f32 v47, v46, v47
	v_cvt_pk_f16_f32 v46, v44, v45
	v_mad_i64_i32 v[44:45], s[6:7], v48, s87, v[60:61]
	v_cvt_pk_f16_f32 v31, v30, v31
	v_cvt_pk_f16_f32 v30, v28, v29
	v_mad_i64_i32 v[28:29], s[6:7], v32, s87, v[60:61]
	v_cvt_pk_f16_f32 v15, v14, v15
	v_cvt_pk_f16_f32 v14, v12, v13
	v_mad_i64_i32 v[12:13], s[6:7], v16, s87, v[60:61]
	s_add_i32 s3, s3, s85
	s_add_i32 s86, s86, s28
	v_lshl_add_u64 v[68:69], v[68:69], 0, v[66:67]
	v_cvt_pk_f16_f32 v59, v58, v59
	v_cvt_pk_f16_f32 v58, v56, v57
	v_cvt_pk_f16_f32 v55, v54, v55
	v_cvt_pk_f16_f32 v54, v52, v53
	v_lshl_add_u64 v[44:45], v[44:45], 0, v[66:67]
	v_cvt_pk_f16_f32 v43, v42, v43
	v_cvt_pk_f16_f32 v42, v40, v41
	v_cvt_pk_f16_f32 v39, v38, v39
	v_cvt_pk_f16_f32 v38, v36, v37
	v_lshl_add_u64 v[28:29], v[28:29], 0, v[66:67]
	v_cvt_pk_f16_f32 v27, v26, v27
	v_cvt_pk_f16_f32 v26, v24, v25
	v_cvt_pk_f16_f32 v23, v22, v23
	v_cvt_pk_f16_f32 v22, v20, v21
	v_lshl_add_u64 v[12:13], v[12:13], 0, v[66:67]
	v_cvt_pk_f16_f32 v11, v10, v11
	v_cvt_pk_f16_f32 v10, v8, v9
	v_cvt_pk_f16_f32 v7, v6, v7
	v_cvt_pk_f16_f32 v6, v4, v5
	v_cvt_pk_f16_f32 v3, v2, v3
	v_cvt_pk_f16_f32 v2, v0, v1
	s_cmpk_gt_i32 s3, 0x1fd
	s_waitcnt vmcnt(0)
	s_barrier
	v_mov_b32_e32 v196, v62
	v_mov_b32_e32 v197, v63
	v_mov_b32_e32 v198, v58
	v_mov_b32_e32 v199, v59
	v_mov_b32_e32 v200, v54
	v_mov_b32_e32 v201, v55
	v_mov_b32_e32 v202, v50
	v_mov_b32_e32 v203, v51
	v_mov_b32_e32 v204, v46
	v_mov_b32_e32 v205, v47
	v_mov_b32_e32 v206, v42
	v_mov_b32_e32 v207, v43
	v_mov_b32_e32 v208, v38
	v_mov_b32_e32 v209, v39
	v_mov_b32_e32 v210, v34
	v_mov_b32_e32 v211, v35
	v_mov_b32_e32 v212, v30
	v_mov_b32_e32 v213, v31
	v_mov_b32_e32 v214, v26
	v_mov_b32_e32 v215, v27
	v_mov_b32_e32 v216, v22
	v_mov_b32_e32 v217, v23
	v_mov_b32_e32 v218, v18
	v_mov_b32_e32 v219, v19
	v_mov_b32_e32 v220, v14
	v_mov_b32_e32 v221, v15
	v_mov_b32_e32 v222, v10
	v_mov_b32_e32 v223, v11
	v_mov_b32_e32 v224, v6
	v_mov_b32_e32 v225, v7
	v_mov_b32_e32 v226, v2
	v_mov_b32_e32 v227, v3
	v_mov_b32_e32 v228, v68
	v_mov_b32_e32 v229, v69
	v_mov_b32_e32 v230, v44
	v_mov_b32_e32 v231, v45
	v_mov_b32_e32 v232, v28
	v_mov_b32_e32 v233, v29
	v_mov_b32_e32 v234, v12
	v_mov_b32_e32 v235, v13
	s_mov_b32 s101, 1
	s_cbranch_scc1 .LBB0_158

.LBB0_156:
	s_waitcnt vmcnt(0)
	s_waitcnt vmcnt(0) lgkmcnt(0)
	s_barrier
	s_add_i32 m0, s100, 0x8000
	s_nop 0
	global_load_lds_dwordx4 v74, s[10:11]
	s_add_i32 m0, s100, 0x9000
	s_nop 0
	global_load_lds_dwordx4 v76, s[10:11]
	s_add_i32 m0, s100, 0xa000
	s_nop 0
	global_load_lds_dwordx4 v78, s[10:11]
	s_add_i32 m0, s100, 0xb000
	s_nop 0
	global_load_lds_dwordx4 v80, s[10:11]
	s_add_i32 m0, s100, 0xc000
	s_nop 0
	global_load_lds_dwordx4 v66, s[98:99]
	s_add_i32 m0, s100, 0xd000
	s_nop 0
	global_load_lds_dwordx4 v68, s[98:99]
	s_add_i32 m0, s100, 0xe000
	s_nop 0
	global_load_lds_dwordx4 v70, s[98:99]
	s_add_i32 m0, s100, 0xf000
	s_nop 0
	global_load_lds_dwordx4 v72, s[98:99]
	s_add_u32 s10, s10, 0x80
	s_addc_u32 s11, s11, 0
	s_add_u32 s98, s98, 0x80
	s_addc_u32 s99, s99, 0
	s_cmp_eq_u32 s101, 0
	s_cbranch_scc1 .Lds_skip_0
	s_cmp_eq_u32 s7, 0
	s_cbranch_scc1 .Lds0_0
	s_cmp_eq_u32 s7, 4
	s_cbranch_scc1 .Lds1_0
	s_cmp_eq_u32 s7, 8
	s_cbranch_scc1 .Lds2_0
	s_cmp_eq_u32 s7, 12
	s_cbranch_scc1 .Lds3_0
	s_branch .Lds_skip_0
.Lds0_0:
	global_store_dwordx2 v[228:229], v[196:197], off
	global_store_dwordx2 v[228:229], v[198:199], off offset:32
	global_store_dwordx2 v[228:229], v[200:201], off offset:64
	global_store_dwordx2 v[228:229], v[202:203], off offset:96
	s_branch .Lds_skip_0
.Lds1_0:
	global_store_dwordx2 v[230:231], v[204:205], off
	global_store_dwordx2 v[230:231], v[206:207], off offset:32
	global_store_dwordx2 v[230:231], v[208:209], off offset:64
	global_store_dwordx2 v[230:231], v[210:211], off offset:96
	s_branch .Lds_skip_0
.Lds2_0:
	global_store_dwordx2 v[232:233], v[212:213], off
	global_store_dwordx2 v[232:233], v[214:215], off offset:32
	global_store_dwordx2 v[232:233], v[216:217], off offset:64
	global_store_dwordx2 v[232:233], v[218:219], off offset:96
	s_branch .Lds_skip_0
.Lds3_0:
	global_store_dwordx2 v[234:235], v[220:221], off
	global_store_dwordx2 v[234:235], v[222:223], off offset:32
	global_store_dwordx2 v[234:235], v[224:225], off offset:64
	global_store_dwordx2 v[234:235], v[226:227], off offset:96
	s_mov_b32 s101, 0
.Lds_skip_0:
	ds_read_b128 v[120:123], v115
	ds_read_b128 v[124:127], v115 offset:2048
	ds_read_b128 v[128:131], v115 offset:4096
	ds_read_b128 v[132:135], v115 offset:6144
	ds_read_b128 v[136:139], v116 offset:16384
	ds_read_b128 v[140:143], v116 offset:18432
	ds_read_b128 v[144:147], v116 offset:20480
	ds_read_b128 v[148:151], v116 offset:22528
	ds_read_b128 v[152:155], v117
	ds_read_b128 v[156:159], v117 offset:2048
	ds_read_b128 v[160:163], v117 offset:4096
	ds_read_b128 v[164:167], v117 offset:6144
	ds_read_b128 v[168:171], v118 offset:16384
	ds_read_b128 v[176:179], v118 offset:18432
	ds_read_b128 v[180:183], v118 offset:20480
	ds_read_b128 v[184:187], v118 offset:22528
	s_waitcnt lgkmcnt(8)
	v_mfma_f32_16x16x32_f16 v[60:63], v[136:139], v[120:123], v[60:63]
	v_mfma_f32_16x16x32_f16 v[56:59], v[140:143], v[120:123], v[56:59]
	v_mfma_f32_16x16x32_f16 v[52:55], v[144:147], v[120:123], v[52:55]
	v_mfma_f32_16x16x32_f16 v[48:51], v[148:151], v[120:123], v[48:51]
	v_mfma_f32_16x16x32_f16 v[44:47], v[136:139], v[124:127], v[44:47]
	v_mfma_f32_16x16x32_f16 v[40:43], v[140:143], v[124:127], v[40:43]
	v_mfma_f32_16x16x32_f16 v[36:39], v[144:147], v[124:127], v[36:39]
	v_mfma_f32_16x16x32_f16 v[32:35], v[148:151], v[124:127], v[32:35]
	v_mfma_f32_16x16x32_f16 v[120:123], v[136:139], v[128:131], v[28:31]
	v_mfma_f32_16x16x32_f16 v[124:127], v[140:143], v[128:131], v[24:27]
	v_mfma_f32_16x16x32_f16 v[188:191], v[144:147], v[128:131], v[20:23]
	v_mfma_f32_16x16x32_f16 v[128:131], v[148:151], v[128:131], v[16:19]
	v_mfma_f32_16x16x32_f16 v[136:139], v[136:139], v[132:135], v[12:15]
	v_mfma_f32_16x16x32_f16 v[140:143], v[140:143], v[132:135], v[8:11]
	v_mfma_f32_16x16x32_f16 v[144:147], v[144:147], v[132:135], v[4:7]
	v_mfma_f32_16x16x32_f16 v[132:135], v[148:151], v[132:135], v[0:3]
	s_waitcnt lgkmcnt(0)
	v_mfma_f32_16x16x32_f16 v[0:3], v[168:171], v[152:155], v[60:63]
	v_mfma_f32_16x16x32_f16 v[4:7], v[176:179], v[152:155], v[56:59]
	v_mfma_f32_16x16x32_f16 v[8:11], v[180:183], v[152:155], v[52:55]
	v_mfma_f32_16x16x32_f16 v[12:15], v[184:187], v[152:155], v[48:51]
	v_mfma_f32_16x16x32_f16 v[16:19], v[168:171], v[156:159], v[44:47]
	v_mfma_f32_16x16x32_f16 v[20:23], v[176:179], v[156:159], v[40:43]
	v_mfma_f32_16x16x32_f16 v[24:27], v[180:183], v[156:159], v[36:39]
	v_mfma_f32_16x16x32_f16 v[28:31], v[184:187], v[156:159], v[32:35]
	v_mfma_f32_16x16x32_f16 v[32:35], v[168:171], v[160:163], v[120:123]
	v_mfma_f32_16x16x32_f16 v[36:39], v[176:179], v[160:163], v[124:127]
	v_mfma_f32_16x16x32_f16 v[40:43], v[180:183], v[160:163], v[188:191]
	v_mfma_f32_16x16x32_f16 v[44:47], v[184:187], v[160:163], v[128:131]
	v_mfma_f32_16x16x32_f16 v[48:51], v[168:171], v[164:167], v[136:139]
	v_mfma_f32_16x16x32_f16 v[52:55], v[176:179], v[164:167], v[140:143]
	v_mfma_f32_16x16x32_f16 v[56:59], v[180:183], v[164:167], v[144:147]
	v_mfma_f32_16x16x32_f16 v[60:63], v[184:187], v[164:167], v[132:135]
	s_waitcnt vmcnt(0)
	s_cmp_gt_u32 s7, 13
	s_cselect_b64 s[12:13], -1, 0
	s_and_b64 vcc, exec, s[12:13]
	s_waitcnt vmcnt(0)
	s_barrier
	s_cbranch_vccnz .LBB0_155
	s_mov_b32 m0, s100
	s_nop 0
	global_load_lds_dwordx4 v74, s[10:11]
	s_add_i32 m0, s100, 0x1000
	s_nop 0
	global_load_lds_dwordx4 v76, s[10:11]
	s_add_i32 m0, s100, 0x2000
	s_nop 0
	global_load_lds_dwordx4 v78, s[10:11]
	s_add_i32 m0, s100, 0x3000
	s_nop 0
	global_load_lds_dwordx4 v80, s[10:11]
	s_add_i32 m0, s100, 0x4000
	s_nop 0
	global_load_lds_dwordx4 v66, s[98:99]
	s_add_i32 m0, s100, 0x5000
	s_nop 0
	global_load_lds_dwordx4 v68, s[98:99]
	s_add_i32 m0, s100, 0x6000
	s_nop 0
	global_load_lds_dwordx4 v70, s[98:99]
	s_add_i32 m0, s100, 0x7000
	s_nop 0
	global_load_lds_dwordx4 v72, s[98:99]
	s_add_u32 s10, s10, 0x80
	s_addc_u32 s11, s11, 0
	s_add_u32 s98, s98, 0x80
	s_addc_u32 s99, s99, 0
	s_branch .LBB0_155
.LBB0_158:
	s_cmp_eq_u32 s101, 0
	s_cbranch_scc1 .Lfl_skip_0
	global_store_dwordx2 v[228:229], v[196:197], off
	global_store_dwordx2 v[228:229], v[198:199], off offset:32
	global_store_dwordx2 v[228:229], v[200:201], off offset:64
	global_store_dwordx2 v[228:229], v[202:203], off offset:96
	global_store_dwordx2 v[230:231], v[204:205], off
	global_store_dwordx2 v[230:231], v[206:207], off offset:32
	global_store_dwordx2 v[230:231], v[208:209], off offset:64
	global_store_dwordx2 v[230:231], v[210:211], off offset:96
	global_store_dwordx2 v[232:233], v[212:213], off
	global_store_dwordx2 v[232:233], v[214:215], off offset:32
	global_store_dwordx2 v[232:233], v[216:217], off offset:64
	global_store_dwordx2 v[232:233], v[218:219], off offset:96
	global_store_dwordx2 v[234:235], v[220:221], off
	global_store_dwordx2 v[234:235], v[222:223], off offset:32
	global_store_dwordx2 v[234:235], v[224:225], off offset:64
	global_store_dwordx2 v[234:235], v[226:227], off offset:96
	s_mov_b32 s101, 0

.LBB0_1127:
	s_or_b64 exec, exec, s[0:1]
	s_mov_b32 s101, 0
	v_mov_b32_e32 v98, v174
	s_waitcnt lgkmcnt(0)
	v_mov_b32_e32 v0, v174
	s_barrier
	s_and_b64 vcc, exec, s[96:97]
	v_ashrrev_i32_e32 v99, 7, v0
	v_bfe_u32 v100, v0, 6, 1
	s_cbranch_vccnz .LBB0_1136
	s_cmpk_gt_i32 s2, 0xfef
	s_cbranch_scc1 .LBB0_1135
	v_and_b32_e32 v0, 15, v98
	v_lshl_or_b32 v101, v99, 6, v0
	v_lshrrev_b32_e32 v0, 2, v98
	v_and_b32_e32 v0, 12, v0
	v_lshl_or_b32 v102, v100, 6, v0
	v_mov_b32_e32 v65, 0
	s_mov_b64 s[0:1], 0x80
	s_mov_b64 s[4:5], 0x100
	s_movk_i32 s3, 0x1e20
	s_mov_b32 s18, s2
	s_waitcnt vmcnt(0)
	s_branch .LBB0_1131

.LBB0_1139:
	v_lshl_add_u32 v64, s8, 7, v99
	v_lshl_or_b32 v66, s6, 7, v98
	v_cvt_pk_f16_f32 v63, v62, v63
	v_cvt_pk_f16_f32 v62, v60, v61
	v_mov_b64_e32 v[60:61], s[42:43]
	v_ashrrev_i32_e32 v67, 31, v66
	v_cvt_pk_f16_f32 v51, v50, v51
	v_cvt_pk_f16_f32 v50, v48, v49
	v_or_b32_e32 v48, 16, v64
	v_cvt_pk_f16_f32 v35, v34, v35
	v_cvt_pk_f16_f32 v34, v32, v33
	v_or_b32_e32 v32, 32, v64
	v_cvt_pk_f16_f32 v19, v18, v19
	v_cvt_pk_f16_f32 v18, v16, v17
	v_or_b32_e32 v16, 48, v64
	v_mad_i64_i32 v[68:69], s[6:7], v64, s21, v[60:61]
	v_lshlrev_b64 v[66:67], 1, v[66:67]
	v_cvt_pk_f16_f32 v47, v46, v47
	v_cvt_pk_f16_f32 v46, v44, v45
	v_mad_i64_i32 v[44:45], s[6:7], v48, s21, v[60:61]
	v_cvt_pk_f16_f32 v31, v30, v31
	v_cvt_pk_f16_f32 v30, v28, v29
	v_mad_i64_i32 v[28:29], s[6:7], v32, s21, v[60:61]
	v_cvt_pk_f16_f32 v15, v14, v15
	v_cvt_pk_f16_f32 v14, v12, v13
	v_mad_i64_i32 v[12:13], s[6:7], v16, s21, v[60:61]
	s_add_i32 s3, s3, s19
	s_add_i32 s20, s20, s28
	v_lshl_add_u64 v[68:69], v[68:69], 0, v[66:67]
	v_cvt_pk_f16_f32 v59, v58, v59
	v_cvt_pk_f16_f32 v58, v56, v57
	v_cvt_pk_f16_f32 v55, v54, v55
	v_cvt_pk_f16_f32 v54, v52, v53
	v_lshl_add_u64 v[44:45], v[44:45], 0, v[66:67]
	v_cvt_pk_f16_f32 v43, v42, v43
	v_cvt_pk_f16_f32 v42, v40, v41
	v_cvt_pk_f16_f32 v39, v38, v39
	v_cvt_pk_f16_f32 v38, v36, v37
	v_lshl_add_u64 v[28:29], v[28:29], 0, v[66:67]
	v_cvt_pk_f16_f32 v27, v26, v27
	v_cvt_pk_f16_f32 v26, v24, v25
	v_cvt_pk_f16_f32 v23, v22, v23
	v_cvt_pk_f16_f32 v22, v20, v21
	v_lshl_add_u64 v[12:13], v[12:13], 0, v[66:67]
	v_cvt_pk_f16_f32 v11, v10, v11
	v_cvt_pk_f16_f32 v10, v8, v9
	v_cvt_pk_f16_f32 v7, v6, v7
	v_cvt_pk_f16_f32 v6, v4, v5
	v_cvt_pk_f16_f32 v3, v2, v3
	v_cvt_pk_f16_f32 v2, v0, v1
	s_cmpk_gt_i32 s3, 0x1fd
	s_waitcnt vmcnt(0)
	s_barrier
	v_mov_b32_e32 v196, v62
	v_mov_b32_e32 v197, v63
	v_mov_b32_e32 v198, v58
	v_mov_b32_e32 v199, v59
	v_mov_b32_e32 v200, v54
	v_mov_b32_e32 v201, v55
	v_mov_b32_e32 v202, v50
	v_mov_b32_e32 v203, v51
	v_mov_b32_e32 v204, v46
	v_mov_b32_e32 v205, v47
	v_mov_b32_e32 v206, v42
	v_mov_b32_e32 v207, v43
	v_mov_b32_e32 v208, v38
	v_mov_b32_e32 v209, v39
	v_mov_b32_e32 v210, v34
	v_mov_b32_e32 v211, v35
	v_mov_b32_e32 v212, v30
	v_mov_b32_e32 v213, v31
	v_mov_b32_e32 v214, v26
	v_mov_b32_e32 v215, v27
	v_mov_b32_e32 v216, v22
	v_mov_b32_e32 v217, v23
	v_mov_b32_e32 v218, v18
	v_mov_b32_e32 v219, v19
	v_mov_b32_e32 v220, v14
	v_mov_b32_e32 v221, v15
	v_mov_b32_e32 v222, v10
	v_mov_b32_e32 v223, v11
	v_mov_b32_e32 v224, v6
	v_mov_b32_e32 v225, v7
	v_mov_b32_e32 v226, v2
	v_mov_b32_e32 v227, v3
	v_mov_b32_e32 v228, v68
	v_mov_b32_e32 v229, v69
	v_mov_b32_e32 v230, v44
	v_mov_b32_e32 v231, v45
	v_mov_b32_e32 v232, v28
	v_mov_b32_e32 v233, v29
	v_mov_b32_e32 v234, v12
	v_mov_b32_e32 v235, v13
	s_mov_b32 s101, 1
	s_cbranch_scc1 .LBB0_1144
